# 16384 w_ffn_out transpose items moved from phase 4 into the idle tail of the FFN-in phase (WGs 128..255); + last phase-2 stage skips empty token blocks
# baseline (speedup 1.0000x reference)
.LBB0_464:
	s_min_i32 s5, s84, 0x80
	v_readlane_b32 s0, v254, 0
	s_waitcnt vmcnt(0)
	v_lshrrev_b32_e32 v2, 6, v0
	s_mov_b32 s2, s0
	s_cmp_ge_i32 s0, s5
	s_mul_i32 s0, s0, 2
	v_add3_u32 v3, v2, s0, -1
	s_cselect_b64 vcc, -1, 0
	s_sub_i32 s0, s2, s5
	s_mul_i32 s4, s5, 2
	s_lshl_b32 s0, s0, 3
	s_add_i32 s0, s0, s4
	v_readlane_b32 s1, v254, 1
	v_add_u32_e32 v2, s0, v2
	v_add_u32_e32 v31, -64, v0
	s_movk_i32 s7, 0x80
	v_cmp_gt_u32_e64 s[0:1], s7, v31
	v_cndmask_b32_e32 v30, v3, v2, vcc
	s_mov_b32 s6, 0x14200
	s_or_b64 s[0:1], vcc, s[0:1]
	v_cmp_gt_i32_e32 vcc, s6, v30
	s_movk_i32 s3, 0x80
	s_and_b64 s[6:7], s[0:1], vcc
	s_and_saveexec_b64 s[0:1], s[6:7]
	s_cbranch_execz .LBB0_491
	s_sub_i32 s5, s84, s5
	v_lshlrev_b32_e32 v2, 8, v0
	s_lshl_b32 s33, s5, 3
	v_and_b32_e32 v2, 0x1c000, v2
	s_add_i32 s33, s33, s4
	v_add_u32_e32 v7, 0, v2
	v_lshlrev_b32_e32 v2, 4, v0
	v_and_b32_e32 v24, 0x70, v2
	v_lshlrev_b32_e32 v2, 3, v0
	s_add_u32 s6, s66, 0x8100000
	v_and_b32_e32 v2, 56, v2
	s_addc_u32 s7, s67, 0
	v_mul_u32_u24_e32 v6, 0x84, v2
	v_lshlrev_b32_e32 v2, 1, v2
	v_mov_b32_e32 v3, 0
	s_add_u32 s8, s66, 0x93400
	v_lshl_add_u64 v[12:13], s[66:67], 0, v[2:3]
	s_addc_u32 s9, s67, 0
	s_mov_b64 s[12:13], 0x6100000
	s_add_u32 s10, s66, 0xbc000
	v_lshl_add_u64 v[8:9], v[12:13], 0, s[12:13]
	s_mov_b64 s[12:13], 0x5100000
	s_mov_b64 s[4:5], 0x12d00000
	s_addc_u32 s11, s67, 0
	v_lshl_add_u64 v[10:11], v[12:13], 0, s[12:13]
	s_mov_b64 s[12:13], 0x4100000
	v_lshl_add_u64 v[4:5], v[12:13], 0, s[4:5]
	v_lshl_add_u64 v[12:13], v[12:13], 0, s[12:13]
	s_add_u32 s12, s66, 0x100000
	s_addc_u32 s13, s67, 0
	v_readlane_b32 s36, v254, 20
	v_lshrrev_b32_e32 v31, 3, v1
	s_add_u32 s14, s66, 0x8b400
	v_readlane_b32 s40, v254, 24
	v_readlane_b32 s41, v254, 25
	v_add_u32_e32 v26, v7, v24
	v_mul_u32_u24_e32 v27, 0x84, v31
	s_addc_u32 s15, s67, 0
	v_readlane_b32 s42, v254, 26
	v_readlane_b32 s43, v254, 27
	v_readlane_b32 s44, v254, 28
	v_readlane_b32 s45, v254, 29
	v_readlane_b32 s46, v254, 30
	v_readlane_b32 s47, v254, 31
	v_readlane_b32 s48, v254, 32
	v_readlane_b32 s49, v254, 33
	v_readlane_b32 s50, v254, 34
	v_readlane_b32 s51, v254, 35
	s_mov_b64 s[20:21], s[40:41]
	v_lshlrev_b32_e32 v2, 2, v31
	v_lshrrev_b32_e32 v1, 1, v1
	v_and_b32_e32 v40, 1, v0
	s_add_u32 s16, s66, 0xb4000
	v_mov_b32_e32 v25, v3
	v_readlane_b32 s37, v254, 21
	v_readlane_b32 s38, v254, 22
	v_readlane_b32 s39, v254, 23
	s_mov_b64 s[24:25], s[44:45]
	s_mov_b64 s[26:27], s[46:47]
	s_mov_b64 s[28:29], s[48:49]
	s_mov_b64 s[30:31], s[50:51]
	v_add_u32_e32 v44, v26, v27
	v_or_b32_e32 v32, 8, v31
	v_or_b32_e32 v33, 16, v31
	v_or_b32_e32 v34, 24, v31
	v_or_b32_e32 v35, 32, v31
	v_or_b32_e32 v36, 40, v31
	v_or_b32_e32 v37, 48, v31
	v_or_b32_e32 v38, 56, v31
	v_add3_u32 v39, v7, v6, v2
	v_lshlrev_b32_e32 v6, 5, v40
	v_lshl_add_u32 v41, v1, 2, v7
	v_mul_u32_u24_e32 v42, 0x1080, v40
	v_mov_b32_e32 v7, v3
	v_cmp_eq_u32_e64 s[4:5], 0, v40
	s_addc_u32 s17, s67, 0
	v_lshl_add_u64 v[14:15], s[60:61], 0, v[24:25]
	v_lshl_add_u64 v[16:17], s[54:55], 0, v[24:25]
	s_mov_b64 s[22:23], s[42:43]
	v_lshl_add_u64 v[18:19], s[30:31], 0, v[24:25]
	v_lshl_add_u64 v[20:21], s[26:27], 0, v[24:25]
	v_lshl_add_u64 v[22:23], s[24:25], 0, v[24:25]
	v_lshl_add_u64 v[24:25], s[28:29], 0, v[24:25]
	v_lshlrev_b32_e32 v43, 5, v30
	s_lshl_b32 s34, s33, 5
	s_mov_b64 s[18:19], 0
	s_movk_i32 s35, 0x3fff
	s_movk_i32 s36, 0x4fff
	s_movk_i32 s37, 0x5fff
	s_movk_i32 s38, 0x7fff
	s_mov_b32 s39, 0x12bff
	v_add_u32_e32 v45, 0x420, v44
	v_add_u32_e32 v46, 0x428, v44
	v_add_u32_e32 v47, 0x840, v44
	v_add_u32_e32 v48, 0x848, v44
	v_add_u32_e32 v49, 0xc60, v44
	v_add_u32_e32 v50, 0xc68, v44
	s_mov_b32 s40, 0xffff0000
	s_mov_b32 s41, 0xbe83
	s_movk_i32 s42, 0x2b0
	s_movk_i32 s43, 0x2a80
	s_mov_b32 s44, 0x42fe0000
	s_mov_b32 s45, 0xc0c0500
	s_mov_b32 s46, 0x181ff
	v_add_u32_e32 v51, 0x1080, v44
	v_add_u32_e32 v52, 0x1088, v44
	v_add_u32_e32 v53, 0x14a0, v44
	v_add_u32_e32 v54, 0x14a8, v44
	v_add_u32_e32 v55, 0x18c0, v44
	s_branch .LBB0_468

.LBB0_1906:
	s_waitcnt vmcnt(0)
	s_mov_b32 s2, s86
	s_barrier
	v_readlane_b32 s94, v254, 0
	s_nop 3
	s_cmpk_lt_u32 s94, 0x80
	s_cbranch_scc1 .Lwf_done
	v_readlane_b32 s96, v254, 2
	v_readlane_b32 s97, v254, 3
	v_readfirstlane_b32 s95, v0
	s_nop 3
	s_sub_u32 s96, s96, 0x28
	s_subb_u32 s97, s97, 0
	s_load_dwordx2 s[100:101], s[96:97], 0x0
	s_lshr_b32 s95, s95, 6
	s_sub_u32 s94, s94, 0x80
	s_lshl_b32 s94, s94, 3
	s_add_u32 s94, s94, s95
	s_add_u32 s94, s94, 0x1600
	v_and_b32_e32 v2, 63, v0
	v_lshrrev_b32_e32 v3, 3, v2
	v_and_b32_e32 v4, 7, v2
	v_lshlrev_b32_e32 v5, 14, v3
	v_lshl_add_u32 v5, v4, 4, v5
	v_add_u32_e32 v6, 0x0, v5
	v_add_u32_e32 v7, 0x20000, v5
	v_add_u32_e32 v8, 0x40000, v5
	v_add_u32_e32 v9, 0x60000, v5
	v_add_u32_e32 v10, 0x80000, v5
	v_add_u32_e32 v11, 0xa0000, v5
	v_add_u32_e32 v12, 0xc0000, v5
	v_add_u32_e32 v13, 0xe0000, v5
	s_lshl_b32 s95, s95, 14
	v_mul_u32_u24_e32 v14, 0x84, v3
	v_lshl_add_u32 v14, v4, 4, v14
	v_add_u32_e32 v14, s95, v14
	v_mul_u32_u24_e32 v15, 0x420, v4
	v_lshl_add_u32 v15, v3, 2, v15
	v_add_u32_e32 v15, s95, v15
	v_mul_u32_u24_e32 v16, 0x5600, v3
	v_lshl_add_u32 v16, v4, 4, v16
	v_add_u32_e32 v17, 0x2b000, v16
	v_add_u32_e32 v18, 0x56000, v16
	v_add_u32_e32 v19, 0x81000, v16
	s_waitcnt lgkmcnt(0)
	s_lshr_b32 vcc_lo, s94, 7
	s_and_b32 vcc_hi, s94, 0x7f
	s_lshl_b32 vcc_lo, vcc_lo, 20
	s_lshl_b32 vcc_hi, vcc_hi, 7
	s_add_u32 s96, s100, vcc_lo
	s_addc_u32 s97, s101, 0
	s_add_u32 s96, s96, vcc_hi
	s_addc_u32 s97, s97, 0
	global_load_dwordx4 v[20:23], v6, s[96:97]
	global_load_dwordx4 v[24:27], v7, s[96:97]
	global_load_dwordx4 v[28:31], v8, s[96:97]
	global_load_dwordx4 v[32:35], v9, s[96:97]
	global_load_dwordx4 v[36:39], v10, s[96:97]
	global_load_dwordx4 v[40:43], v11, s[96:97]
	global_load_dwordx4 v[44:47], v12, s[96:97]
	global_load_dwordx4 v[48:51], v13, s[96:97]
	s_waitcnt vmcnt(7)
	ds_write_b32 v14, v20 offset:0
	ds_write_b32 v14, v21 offset:4
	ds_write_b32 v14, v22 offset:8
	ds_write_b32 v14, v23 offset:12
	s_waitcnt vmcnt(6)
	ds_write_b32 v14, v24 offset:1056
	ds_write_b32 v14, v25 offset:1060
	ds_write_b32 v14, v26 offset:1064
	ds_write_b32 v14, v27 offset:1068
	s_waitcnt vmcnt(5)
	ds_write_b32 v14, v28 offset:2112
	ds_write_b32 v14, v29 offset:2116
	ds_write_b32 v14, v30 offset:2120
	ds_write_b32 v14, v31 offset:2124
	s_waitcnt vmcnt(4)
	ds_write_b32 v14, v32 offset:3168
	ds_write_b32 v14, v33 offset:3172
	ds_write_b32 v14, v34 offset:3176
	ds_write_b32 v14, v35 offset:3180
	s_waitcnt vmcnt(3)
	ds_write_b32 v14, v36 offset:4224
	ds_write_b32 v14, v37 offset:4228
	ds_write_b32 v14, v38 offset:4232
	ds_write_b32 v14, v39 offset:4236
	s_waitcnt vmcnt(2)
	ds_write_b32 v14, v40 offset:5280
	ds_write_b32 v14, v41 offset:5284
	ds_write_b32 v14, v42 offset:5288
	ds_write_b32 v14, v43 offset:5292
	s_waitcnt vmcnt(1)
	ds_write_b32 v14, v44 offset:6336
	ds_write_b32 v14, v45 offset:6340
	ds_write_b32 v14, v46 offset:6344
	ds_write_b32 v14, v47 offset:6348
	s_waitcnt vmcnt(0)
	ds_write_b32 v14, v48 offset:7392
	ds_write_b32 v14, v49 offset:7396
	ds_write_b32 v14, v50 offset:7400
	ds_write_b32 v14, v51 offset:7404
	s_branch .Lwf_body
.Lwf_loop:
	s_waitcnt vmcnt(11)
	ds_write_b32 v14, v20 offset:0
	ds_write_b32 v14, v21 offset:4
	ds_write_b32 v14, v22 offset:8
	ds_write_b32 v14, v23 offset:12
	s_waitcnt vmcnt(10)
	ds_write_b32 v14, v24 offset:1056
	ds_write_b32 v14, v25 offset:1060
	ds_write_b32 v14, v26 offset:1064
	ds_write_b32 v14, v27 offset:1068
	s_waitcnt vmcnt(9)
	ds_write_b32 v14, v28 offset:2112
	ds_write_b32 v14, v29 offset:2116
	ds_write_b32 v14, v30 offset:2120
	ds_write_b32 v14, v31 offset:2124
	s_waitcnt vmcnt(8)
	ds_write_b32 v14, v32 offset:3168
	ds_write_b32 v14, v33 offset:3172
	ds_write_b32 v14, v34 offset:3176
	ds_write_b32 v14, v35 offset:3180
	s_waitcnt vmcnt(7)
	ds_write_b32 v14, v36 offset:4224
	ds_write_b32 v14, v37 offset:4228
	ds_write_b32 v14, v38 offset:4232
	ds_write_b32 v14, v39 offset:4236
	s_waitcnt vmcnt(6)
	ds_write_b32 v14, v40 offset:5280
	ds_write_b32 v14, v41 offset:5284
	ds_write_b32 v14, v42 offset:5288
	ds_write_b32 v14, v43 offset:5292
	s_waitcnt vmcnt(5)
	ds_write_b32 v14, v44 offset:6336
	ds_write_b32 v14, v45 offset:6340
	ds_write_b32 v14, v46 offset:6344
	ds_write_b32 v14, v47 offset:6348
	s_waitcnt vmcnt(4)
	ds_write_b32 v14, v48 offset:7392
	ds_write_b32 v14, v49 offset:7396
	ds_write_b32 v14, v50 offset:7400
	ds_write_b32 v14, v51 offset:7404
.Lwf_body:
	s_mov_b32 s95, s94
	s_add_u32 s94, s94, 0x400
	s_cmpk_lt_u32 s94, 0x5600
	s_cbranch_scc0 .Lwf_nopf
	s_lshr_b32 vcc_lo, s94, 7
	s_and_b32 vcc_hi, s94, 0x7f
	s_lshl_b32 vcc_lo, vcc_lo, 20
	s_lshl_b32 vcc_hi, vcc_hi, 7
	s_add_u32 s96, s100, vcc_lo
	s_addc_u32 s97, s101, 0
	s_add_u32 s96, s96, vcc_hi
	s_addc_u32 s97, s97, 0
	global_load_dwordx4 v[20:23], v6, s[96:97]
	global_load_dwordx4 v[24:27], v7, s[96:97]
	global_load_dwordx4 v[28:31], v8, s[96:97]
	global_load_dwordx4 v[32:35], v9, s[96:97]
	global_load_dwordx4 v[36:39], v10, s[96:97]
	global_load_dwordx4 v[40:43], v11, s[96:97]
	global_load_dwordx4 v[44:47], v12, s[96:97]
	global_load_dwordx4 v[48:51], v13, s[96:97]
.Lwf_nopf:
	ds_read2_b32 v[52:53], v15 offset0:0 offset1:33
	ds_read2_b32 v[54:55], v15 offset0:66 offset1:99
	ds_read2_b32 v[56:57], v15 offset0:132 offset1:165
	ds_read2_b32 v[58:59], v15 offset0:198 offset1:231
	ds_read2_b32 v[60:61], v15 offset0:8 offset1:41
	ds_read2_b32 v[62:63], v15 offset0:74 offset1:107
	ds_read2_b32 v[64:65], v15 offset0:140 offset1:173
	ds_read2_b32 v[66:67], v15 offset0:206 offset1:239
	ds_read2_b32 v[68:69], v15 offset0:16 offset1:49
	ds_read2_b32 v[70:71], v15 offset0:82 offset1:115
	ds_read2_b32 v[72:73], v15 offset0:148 offset1:181
	ds_read2_b32 v[74:75], v15 offset0:214 offset1:247
	ds_read2_b32 v[76:77], v15 offset0:24 offset1:57
	ds_read2_b32 v[78:79], v15 offset0:90 offset1:123
	ds_read2_b32 v[80:81], v15 offset0:156 offset1:189
	ds_read2_b32 v[82:83], v15 offset0:222 offset1:255
	s_lshr_b32 vcc_lo, s95, 7
	s_and_b32 vcc_hi, s95, 0x7f
	s_mul_i32 vcc_hi, vcc_hi, 0xac000
	s_lshl_b32 vcc_lo, vcc_lo, 7
	s_add_u32 s98, s66, 0x12d00000
	s_addc_u32 s99, s67, 0
	s_add_u32 s98, s98, vcc_hi
	s_addc_u32 s99, s99, 0
	s_add_u32 s98, s98, vcc_lo
	s_addc_u32 s99, s99, 0
	s_waitcnt lgkmcnt(0)
	v_cvt_pk_bf16_f32 v84, v52, v53
	v_cvt_pk_bf16_f32 v85, v54, v55
	v_cvt_pk_bf16_f32 v86, v56, v57
	v_cvt_pk_bf16_f32 v87, v58, v59
	v_cvt_pk_bf16_f32 v88, v60, v61
	v_cvt_pk_bf16_f32 v89, v62, v63
	v_cvt_pk_bf16_f32 v90, v64, v65
	v_cvt_pk_bf16_f32 v91, v66, v67
	v_cvt_pk_bf16_f32 v92, v68, v69
	v_cvt_pk_bf16_f32 v93, v70, v71
	v_cvt_pk_bf16_f32 v94, v72, v73
	v_cvt_pk_bf16_f32 v95, v74, v75
	v_cvt_pk_bf16_f32 v96, v76, v77
	v_cvt_pk_bf16_f32 v97, v78, v79
	v_cvt_pk_bf16_f32 v98, v80, v81
	v_cvt_pk_bf16_f32 v99, v82, v83
	global_store_dwordx4 v16, v[84:87], s[98:99]
	global_store_dwordx4 v17, v[88:91], s[98:99]
	global_store_dwordx4 v18, v[92:95], s[98:99]
	global_store_dwordx4 v19, v[96:99], s[98:99]
	s_cmpk_lt_u32 s94, 0x5600
	s_cbranch_scc1 .Lwf_loop
.Lwf_done:
	s_cmp_lt_u32 s93, 18
	s_cbranch_scc1 .LBB0_1960

	.amdhsa_kernel _Z10fwd_kernel1P
		.amdhsa_group_segment_fixed_size 0
		.amdhsa_private_segment_fixed_size 0
		.amdhsa_kernarg_size 520
		.amdhsa_user_sgpr_count 2
		.amdhsa_user_sgpr_dispatch_ptr 0
		.amdhsa_user_sgpr_queue_ptr 0
		.amdhsa_user_sgpr_kernarg_segment_ptr 1
		.amdhsa_user_sgpr_dispatch_id 0
		.amdhsa_user_sgpr_kernarg_preload_length 0
		.amdhsa_user_sgpr_kernarg_preload_offset 0
		.amdhsa_user_sgpr_private_segment_size 0
		.amdhsa_uses_dynamic_stack 0
		.amdhsa_enable_private_segment 0
		.amdhsa_system_sgpr_workgroup_id_x 1
		.amdhsa_system_sgpr_workgroup_id_y 0
		.amdhsa_system_sgpr_workgroup_id_z 0
		.amdhsa_system_sgpr_workgroup_info 0
		.amdhsa_system_vgpr_workitem_id 0
		.amdhsa_next_free_vgpr 256
		.amdhsa_next_free_sgpr 102
		.amdhsa_accum_offset 256
		.amdhsa_reserve_vcc 1
		.amdhsa_float_round_mode_32 0
		.amdhsa_float_round_mode_16_64 0
		.amdhsa_float_denorm_mode_32 3
		.amdhsa_float_denorm_mode_16_64 3
		.amdhsa_dx10_clamp 1
		.amdhsa_ieee_mode 1
		.amdhsa_fp16_overflow 0
		.amdhsa_tg_split 0
		.amdhsa_exception_fp_ieee_invalid_op 0
		.amdhsa_exception_fp_denorm_src 0
		.amdhsa_exception_fp_ieee_div_zero 0
		.amdhsa_exception_fp_ieee_overflow 0
		.amdhsa_exception_fp_ieee_underflow 0
		.amdhsa_exception_fp_ieee_inexact 0
		.amdhsa_exception_int_div_zero 0
	.end_amdhsa_kernel

amdhsa.kernels:
  - .agpr_count:     0
    .args:
      - .offset:         0
        .size:           264
        .value_kind:     by_value
      - .offset:         264
        .size:           4
        .value_kind:     hidden_block_count_x
      - .offset:         268
        .size:           4
        .value_kind:     hidden_block_count_y
      - .offset:         272
        .size:           4
        .value_kind:     hidden_block_count_z
      - .offset:         276
        .size:           2
        .value_kind:     hidden_group_size_x
      - .offset:         278
        .size:           2
        .value_kind:     hidden_group_size_y
      - .offset:         280
        .size:           2
        .value_kind:     hidden_group_size_z
      - .offset:         282
        .size:           2
        .value_kind:     hidden_remainder_x
      - .offset:         284
        .size:           2
        .value_kind:     hidden_remainder_y
      - .offset:         286
        .size:           2
        .value_kind:     hidden_remainder_z
      - .offset:         304
        .size:           8
        .value_kind:     hidden_global_offset_x
      - .offset:         312
        .size:           8
        .value_kind:     hidden_global_offset_y
      - .offset:         320
        .size:           8
        .value_kind:     hidden_global_offset_z
      - .offset:         328
        .size:           2
        .value_kind:     hidden_grid_dims
      - .offset:         384
        .size:           4
        .value_kind:     hidden_dynamic_lds_size
    .group_segment_fixed_size: 0
    .kernarg_segment_align: 8
    .kernarg_segment_size: 520
    .language:       OpenCL C
    .language_version:
      - 2
      - 0
    .max_flat_workgroup_size: 512
    .name:           _Z10fwd_kernel1P
    .private_segment_fixed_size: 0
    .sgpr_count:     108
    .sgpr_spill_count: 80
    .symbol:         _Z10fwd_kernel1P.kd
    .uniform_work_group_size: 1
    .uses_dynamic_stack: false
    .vgpr_count:     256
    .vgpr_spill_count: 0
    .wavefront_size: 64
